# v87 + attention loops: rescale block out of line (keep path falls through), alpha applied to l inside the rescale block, redundant branch over empty skip stub removed
# speedup vs baseline: 1.0023x; 1.0023x over previous
; #define LAS __attribute__((address_space(3)))
; DI float shfl_xor_l(float v, int lane, int m) { return __int_as_float(__builtin_amdgcn_ds_bpermute((lane ^ m) << 2, __float_as_int(v))); }
; #define A_LOAD(kt) do { const size_t ko = (size_t)(kt) * 64; st0 = *(const u32x4*)(kn_src + ko * 2048); st1 = *(const u32x4*)(kn_src + (ko + 32) * 2048); \
;         st2 = *(const u32x4*)(kr_src + ko * 64); st3 = *(const u32x4*)(v_src + ko); st4 = *(const u32x4*)(v_src + ko + (size_t)64 * 8192); } while (0)
; #define VLD(dst, j, dt) do { LAS unsigned char* va_ = vb + (32 * (dt) + n) * VROW + (16 * (j) + 4 * g) * 2; const u32x2 lo_ = *(const LAS u32x2*)(va_), hi_ = *(const LAS u32x2*)(va_ + 16); dst = (u32x4){lo_.x, lo_.y, hi_.x, hi_.y}; } while (0)
; DI void attn_unit(LAS unsigned char* lds, int wid, int b, int h, int qb) {
;     ...
;         if (kt + 1 < nkt) A_LOAD(kt + 1);
;         if (kt <= cq) {
;             LAS unsigned char* kb = lds + buf * ABUF; LAS unsigned char* vb = kb + KBYTES;
;             f32x16 s0, s1;
; #pragma unroll
;             for (int i = 0; i < 16; ++i) { s0[i] = 0.f; s1[i] = 0.f; }
;     ...
;             bf16x8 ka[3][2];
;             ka[0][0] = KLD(0, 0); ka[0][1] = KLD(0, 1); ka[1][0] = KLD(1, 0); ka[1][1] = KLD(1, 1);
; #pragma unroll
;             for (int ks = 0; ks < 12; ++ks) {
;                 if (ks + 2 < 12) { ka[(ks + 2) % 3][0] = KLD(ks + 2, 0); ka[(ks + 2) % 3][1] = KLD(ks + 2, 1); }
;                 s0 = __builtin_amdgcn_mfma_f32_32x32x16_bf16(ka[ks % 3][0], qf[ks], s0, 0, 0, 0); s1 = __builtin_amdgcn_mfma_f32_32x32x16_bf16(ka[ks % 3][1], qf[ks], s1, 0, 0, 0);
;                 __builtin_amdgcn_sched_barrier(0); }
;             u32x4 vf[2][4];
; #pragma unroll
;             for (int dt = 0; dt < 4; ++dt) VLD(vf[0][dt], 0, dt);
;             float mx = s0[0];
; #pragma unroll
;             for (int i = 1; i < 16; ++i) mx = fmaxf(mx, s0[i]);
; #pragma unroll
;             for (int i = 0; i < 16; ++i) mx = fmaxf(mx, s1[i]);
;             mx = fmaxf(mx, shfl_xor_l(mx, lane, 32));
;             const float mnew = fmaxf(mrow, mx), alpha = __builtin_amdgcn_exp2f(mrow - mnew); mrow = mnew;
;             float ls = 0.f;
; #pragma unroll
;             for (int i = 0; i < 16; ++i) { s0[i] = __builtin_amdgcn_exp2f(s0[i] - mnew); s1[i] = __builtin_amdgcn_exp2f(s1[i] - mnew); ls += s0[i] + s1[i]; }
.LBB0_1079:
	s_and_b32 s65, s64, 1
	global_load_dwordx4 v[146:149], v194, s[70:71]
	global_load_dwordx4 v[150:153], v194, s[72:73]
	global_load_dwordx4 v[154:157], v192, s[78:79]
	global_load_dwordx4 v[158:161], v190, s[74:75] offset:128
	global_load_dwordx4 v[162:165], v190, s[76:77] offset:128
	s_cmp_gt_u32 s64, s62
	s_cbranch_scc1 .LBB0_1083
	s_mul_i32 s66, s65, 0xa800
	s_add_i32 s66, s66, 0
	v_add3_u32 v171, s66, v199, v202
	ds_read_b128 v[66:69], v171
	ds_read_b128 v[166:169], v171 offset:32
	ds_read_b128 v[82:85], v171 offset:12800
	ds_read_b128 v[172:175], v171 offset:64
	ds_read_b128 v[176:179], v171 offset:12832
	ds_read_b128 v[204:207], v171 offset:12864
	s_waitcnt lgkmcnt(3)
	v_mfma_f32_32x32x16_bf16 v[82:97], v[82:85], v[142:145], v[216:231]
	v_mfma_f32_32x32x16_bf16 v[66:81], v[66:69], v[142:145], v[216:231]
	v_mfma_f32_32x32x16_bf16 v[66:81], v[166:169], v[138:141], v[66:81]
	ds_read_b128 v[166:169], v171 offset:96
	ds_read_b128 v[208:211], v171 offset:12896
	s_waitcnt lgkmcnt(3)
	v_mfma_f32_32x32x16_bf16 v[82:97], v[176:179], v[138:141], v[82:97]
	v_mfma_f32_32x32x16_bf16 v[66:81], v[172:175], v[134:137], v[66:81]
	ds_read_b128 v[172:175], v171 offset:128
	ds_read_b128 v[176:179], v171 offset:12928
	s_waitcnt lgkmcnt(4)
	v_mfma_f32_32x32x16_bf16 v[82:97], v[204:207], v[134:137], v[82:97]
	s_waitcnt lgkmcnt(3)
	v_mfma_f32_32x32x16_bf16 v[66:81], v[166:169], v[130:133], v[66:81]
	ds_read_b128 v[166:169], v171 offset:160
	ds_read_b128 v[204:207], v171 offset:12960
	s_waitcnt lgkmcnt(4)
	v_mfma_f32_32x32x16_bf16 v[82:97], v[208:211], v[130:133], v[82:97]
	s_waitcnt lgkmcnt(3)
	v_mfma_f32_32x32x16_bf16 v[66:81], v[172:175], v[126:129], v[66:81]
	ds_read_b128 v[172:175], v171 offset:192
	ds_read_b128 v[208:211], v171 offset:12992
	s_waitcnt lgkmcnt(4)
	v_mfma_f32_32x32x16_bf16 v[82:97], v[176:179], v[126:129], v[82:97]
	s_waitcnt lgkmcnt(3)
	v_mfma_f32_32x32x16_bf16 v[66:81], v[166:169], v[122:125], v[66:81]
	ds_read_b128 v[166:169], v171 offset:224
	ds_read_b128 v[176:179], v171 offset:13024
	s_waitcnt lgkmcnt(4)
	v_mfma_f32_32x32x16_bf16 v[82:97], v[204:207], v[122:125], v[82:97]
	s_waitcnt lgkmcnt(3)
	v_mfma_f32_32x32x16_bf16 v[66:81], v[172:175], v[118:121], v[66:81]
	ds_read_b128 v[172:175], v171 offset:256
	ds_read_b128 v[204:207], v171 offset:13056
	s_waitcnt lgkmcnt(4)
	v_mfma_f32_32x32x16_bf16 v[82:97], v[208:211], v[118:121], v[82:97]
	s_waitcnt lgkmcnt(3)
	v_mfma_f32_32x32x16_bf16 v[66:81], v[166:169], v[114:117], v[66:81]
	ds_read_b128 v[166:169], v171 offset:288
	ds_read_b128 v[208:211], v171 offset:13088
	s_waitcnt lgkmcnt(4)
	v_mfma_f32_32x32x16_bf16 v[82:97], v[176:179], v[114:117], v[82:97]
	s_waitcnt lgkmcnt(3)
	v_mfma_f32_32x32x16_bf16 v[66:81], v[172:175], v[110:113], v[66:81]
	ds_read_b128 v[172:175], v171 offset:320
	ds_read_b128 v[176:179], v171 offset:13120
	s_waitcnt lgkmcnt(4)
	v_mfma_f32_32x32x16_bf16 v[82:97], v[204:207], v[110:113], v[82:97]
	s_waitcnt lgkmcnt(3)
	v_mfma_f32_32x32x16_bf16 v[66:81], v[166:169], v[106:109], v[66:81]
	ds_read_b128 v[166:169], v171 offset:352
	ds_read_b128 v[212:215], v171 offset:13152
	s_waitcnt lgkmcnt(4)
	v_mfma_f32_32x32x16_bf16 v[82:97], v[208:211], v[106:109], v[82:97]
	s_waitcnt lgkmcnt(3)
	v_mfma_f32_32x32x16_bf16 v[66:81], v[172:175], v[102:105], v[66:81]
	s_waitcnt lgkmcnt(2)
	v_mfma_f32_32x32x16_bf16 v[82:97], v[176:179], v[102:105], v[82:97]
	s_waitcnt lgkmcnt(1)
	v_mfma_f32_32x32x16_bf16 v[66:81], v[166:169], v[98:101], v[66:81]
	v_add_u32_e32 v171, s66, v184
	v_add_u32_e32 v171, v171, v189
	v_add_u32_e32 v204, 0x6000, v171
	v_add_u32_e32 v205, 0x7000, v171
	v_add_u32_e32 v206, 0x8000, v171
	v_add_u32_e32 v207, 0x9000, v171
	ds_read2_b64 v[166:169], v204 offset0:128 offset1:130
	s_nop 4
	v_max_f32_e32 v172, v66, v67
	s_waitcnt lgkmcnt(1)
	v_mfma_f32_32x32x16_bf16 v[82:97], v[212:215], v[98:101], v[82:97]
	v_max3_f32 v172, v172, v68, v69
	v_max3_f32 v172, v172, v70, v71
	v_max3_f32 v172, v172, v72, v73
	v_max3_f32 v172, v172, v74, v75
	v_max3_f32 v172, v172, v76, v77
	v_max3_f32 v172, v172, v78, v79
	v_max3_f32 v172, v172, v80, v81
	s_nop 4
	v_max3_f32 v172, v172, v82, v83
	v_max3_f32 v172, v172, v84, v85
	v_max3_f32 v172, v172, v86, v87
	v_max3_f32 v172, v172, v88, v89
	v_max3_f32 v172, v172, v90, v91
	v_max3_f32 v172, v172, v92, v93
	v_max3_f32 v172, v172, v94, v95
	v_max3_f32 v172, v172, v96, v97
	ds_bpermute_b32 v173, v185, v172
	ds_read2_b64 v[178:181], v205 offset0:160 offset1:162
	ds_read2_b64 v[174:177], v206 offset0:192 offset1:194
	s_waitcnt lgkmcnt(2)
	v_max_f32_e32 v237, v172, v173
	v_cmp_lt_f32_e32 vcc, 0x41000000, v237
	ds_read2_b64 v[170:173], v207 offset0:224 offset1:226
	s_cmp_eq_u32 s64, 0
	s_cbranch_scc1 .Lfold_0_upd
	s_cbranch_vccnz .Lfold_0_upd
.LBB0_1082:
	v_exp_f32_e32 v66, v66
	v_exp_f32_e32 v82, v82
	v_exp_f32_e32 v67, v67
	v_exp_f32_e32 v83, v83
	v_exp_f32_e32 v68, v68
	v_exp_f32_e32 v84, v84
	v_exp_f32_e32 v69, v69
	v_exp_f32_e32 v85, v85
	v_add_f32_e32 v208, v82, v66
	v_exp_f32_e32 v70, v70
	v_exp_f32_e32 v86, v86

; DI unsigned pk2(float a, float b) { f32x2 f = {a, b}; bf16v2 r = __builtin_convertvector(f, bf16v2); return __builtin_bit_cast(unsigned, r); }
; #define VLD(dst, j, dt) do { LAS unsigned char* va_ = vb + (32 * (dt) + n) * VROW + (16 * (j) + 4 * g) * 2; const u32x2 lo_ = *(const LAS u32x2*)(va_), hi_ = *(const LAS u32x2*)(va_ + 16); dst = (u32x4){lo_.x, lo_.y, hi_.x, hi_.y}; } while (0)
; DI void attn_unit(LAS unsigned char* lds, int wid, int b, int h, int qb) {
;     ...
;             for (int i = 0; i < 16; ++i) { s0[i] = __builtin_amdgcn_exp2f(s0[i] - mnew); s1[i] = __builtin_amdgcn_exp2f(s1[i] - mnew); ls += s0[i] + s1[i]; }
;             lrow = lrow * alpha + ls;
;             if (__builtin_amdgcn_ballot_w64(alpha != 1.f) != 0ull) {
; #pragma unroll
;                 for (int dt = 0; dt < 4; ++dt)
; #pragma unroll
;                     for (int i = 0; i < 16; ++i) o[dt][i] *= alpha;
;             }
;             bf16x8 pf[4];
; #pragma unroll
;             for (int jj = 0; jj < 2; ++jj) { u32x4 w0, w1;
;                 w0.x = pk2(s0[8 * jj + 0], s0[8 * jj + 1]); w0.y = pk2(s0[8 * jj + 2], s0[8 * jj + 3]); w0.z = pk2(s0[8 * jj + 4], s0[8 * jj + 5]); w0.w = pk2(s0[8 * jj + 6], s0[8 * jj + 7]);
;                 w1.x = pk2(s1[8 * jj + 0], s1[8 * jj + 1]); w1.y = pk2(s1[8 * jj + 2], s1[8 * jj + 3]); w1.z = pk2(s1[8 * jj + 4], s1[8 * jj + 5]); w1.w = pk2(s1[8 * jj + 6], s1[8 * jj + 7]);
;                 pf[jj] = __builtin_bit_cast(bf16x8, w0); pf[2 + jj] = __builtin_bit_cast(bf16x8, w1); }
; #pragma unroll
;             for (int j = 0; j < 4; ++j) {
;                 if (j < 3) {
; #pragma unroll
;                     for (int dt = 0; dt < 4; ++dt) VLD(vf[(j + 1) & 1][dt], j + 1, dt);
;                 }
; #pragma unroll
;                 for (int dt = 0; dt < 4; ++dt) o[dt] = __builtin_amdgcn_mfma_f32_32x32x16_bf16(__builtin_bit_cast(bf16x8, vf[j & 1][dt]), pf[j], o[dt], 0, 0, 0);
;                 __builtin_amdgcn_sched_barrier(0); }
	v_add_f32_e32 v209, v83, v67
	v_exp_f32_e32 v71, v71
	v_exp_f32_e32 v87, v87
	v_add_f32_e32 v208, v209, v208
	v_add_f32_e32 v209, v84, v68
	v_exp_f32_e32 v72, v72
	v_exp_f32_e32 v88, v88
	v_add_f32_e32 v208, v209, v208
	v_add_f32_e32 v209, v85, v69
	v_exp_f32_e32 v73, v73
	v_exp_f32_e32 v89, v89
	v_add_f32_e32 v208, v209, v208
	v_add_f32_e32 v209, v86, v70
	v_exp_f32_e32 v74, v74
	v_exp_f32_e32 v90, v90
	v_add_f32_e32 v208, v209, v208
	v_add_f32_e32 v209, v87, v71
	v_exp_f32_e32 v75, v75
	v_exp_f32_e32 v91, v91
	v_add_f32_e32 v208, v209, v208
	v_add_f32_e32 v209, v88, v72
	v_exp_f32_e32 v76, v76
	v_exp_f32_e32 v92, v92
	v_add_f32_e32 v208, v209, v208
	v_add_f32_e32 v209, v89, v73
	v_exp_f32_e32 v77, v77
	v_exp_f32_e32 v93, v93
	v_add_f32_e32 v208, v209, v208
	v_add_f32_e32 v209, v90, v74
	v_exp_f32_e32 v78, v78
	v_exp_f32_e32 v94, v94
	v_add_f32_e32 v208, v209, v208
	v_add_f32_e32 v209, v91, v75
	v_exp_f32_e32 v79, v79
	v_exp_f32_e32 v95, v95
	v_add_f32_e32 v208, v209, v208
	v_add_f32_e32 v209, v92, v76
	v_exp_f32_e32 v80, v80
	v_exp_f32_e32 v96, v96
	v_add_f32_e32 v208, v209, v208
	v_add_f32_e32 v209, v93, v77
	v_exp_f32_e32 v81, v81
	v_exp_f32_e32 v97, v97
	v_add_f32_e32 v208, v209, v208
	v_add_f32_e32 v209, v94, v78
	v_add_f32_e32 v208, v209, v208
	v_add_f32_e32 v209, v95, v79
	v_add_f32_e32 v208, v209, v208
	v_cvt_pk_bf16_f32 v66, v66, v67
	v_cvt_pk_bf16_f32 v67, v68, v69
	v_cvt_pk_bf16_f32 v68, v70, v71
	v_cvt_pk_bf16_f32 v69, v72, v73
	v_add_f32_e32 v70, v96, v80
	v_add_f32_e32 v70, v70, v208
	v_mfma_f32_32x32x16_bf16 v[50:65], v[166:169], v[66:69], v[50:65]
	v_add_f32_e32 v71, v97, v81
	v_add_f32_e32 v166, v71, v70
	v_cvt_pk_bf16_f32 v70, v82, v83
	v_cvt_pk_bf16_f32 v71, v84, v85
	v_cvt_pk_bf16_f32 v72, v86, v87
	v_cvt_pk_bf16_f32 v73, v88, v89
	v_cvt_pk_bf16_f32 v74, v74, v75
	s_waitcnt lgkmcnt(2)
	v_mfma_f32_32x32x16_bf16 v[34:49], v[178:181], v[66:69], v[34:49]
	v_cvt_pk_bf16_f32 v75, v76, v77
	v_cvt_pk_bf16_f32 v76, v78, v79
	v_cvt_pk_bf16_f32 v77, v80, v81
	v_cvt_pk_bf16_f32 v78, v90, v91
	v_cvt_pk_bf16_f32 v79, v92, v93
	v_cvt_pk_bf16_f32 v80, v94, v95
	v_cvt_pk_bf16_f32 v81, v96, v97
	s_waitcnt lgkmcnt(1)
	v_mfma_f32_32x32x16_bf16 v[18:33], v[174:177], v[66:69], v[18:33]
	ds_read2_b64 v[82:85], v204 offset0:132 offset1:134
	ds_read2_b64 v[86:89], v205 offset0:164 offset1:166
	ds_read2_b64 v[90:93], v206 offset0:196 offset1:198
	ds_read2_b64 v[94:97], v207 offset0:228 offset1:230
	v_add_f32_e32 v187, v187, v166
	s_waitcnt lgkmcnt(4)
	v_mfma_f32_32x32x16_bf16 v[2:17], v[170:173], v[66:69], v[2:17]
	s_waitcnt lgkmcnt(3)
	v_mfma_f32_32x32x16_bf16 v[50:65], v[82:85], v[74:77], v[50:65]
	s_waitcnt lgkmcnt(2)
	v_mfma_f32_32x32x16_bf16 v[34:49], v[86:89], v[74:77], v[34:49]
	s_waitcnt lgkmcnt(1)
	v_mfma_f32_32x32x16_bf16 v[18:33], v[90:93], v[74:77], v[18:33]
	ds_read2_b64 v[66:69], v204 offset0:136 offset1:138
	ds_read2_b64 v[82:85], v205 offset0:168 offset1:170
	ds_read2_b64 v[86:89], v206 offset0:200 offset1:202
	ds_read2_b64 v[90:93], v207 offset0:232 offset1:234
	s_waitcnt lgkmcnt(4)
	v_mfma_f32_32x32x16_bf16 v[2:17], v[94:97], v[74:77], v[2:17]
	s_waitcnt lgkmcnt(3)
	v_mfma_f32_32x32x16_bf16 v[50:65], v[66:69], v[70:73], v[50:65]
	s_waitcnt lgkmcnt(2)
	v_mfma_f32_32x32x16_bf16 v[34:49], v[82:85], v[70:73], v[34:49]
	s_waitcnt lgkmcnt(1)
	v_mfma_f32_32x32x16_bf16 v[18:33], v[86:89], v[70:73], v[18:33]
	ds_read2_b64 v[66:69], v204 offset0:140 offset1:142
	ds_read2_b64 v[74:77], v205 offset0:172 offset1:174
	ds_read2_b64 v[82:85], v206 offset0:204 offset1:206
	ds_read2_b64 v[86:89], v207 offset0:236 offset1:238
	s_waitcnt lgkmcnt(4)
	v_mfma_f32_32x32x16_bf16 v[2:17], v[90:93], v[70:73], v[2:17]
	s_waitcnt lgkmcnt(3)
	v_mfma_f32_32x32x16_bf16 v[50:65], v[66:69], v[78:81], v[50:65]
	s_waitcnt lgkmcnt(2)
	v_mfma_f32_32x32x16_bf16 v[34:49], v[74:77], v[78:81], v[34:49]
	s_waitcnt lgkmcnt(1)
	v_mfma_f32_32x32x16_bf16 v[18:33], v[82:85], v[78:81], v[18:33]
	s_waitcnt lgkmcnt(0)
	v_mfma_f32_32x32x16_bf16 v[2:17], v[86:89], v[78:81], v[2:17]

; DI void attn_unit(LAS unsigned char* lds, int wid, int b, int h, int qb) {
;     ...
;             const float mnew = fmaxf(mrow, mx), alpha = __builtin_amdgcn_exp2f(mrow - mnew); mrow = mnew;
;             float ls = 0.f;
; #pragma unroll
;             for (int i = 0; i < 16; ++i) { s0[i] = __builtin_amdgcn_exp2f(s0[i] - mnew); s1[i] = __builtin_amdgcn_exp2f(s1[i] - mnew); ls += s0[i] + s1[i]; }
;             lrow = lrow * alpha + ls;
;             if (__builtin_amdgcn_ballot_w64(alpha != 1.f) != 0ull) {
; #pragma unroll
;                 for (int dt = 0; dt < 4; ++dt)
; #pragma unroll
;                     for (int i = 0; i < 16; ++i) o[dt][i] *= alpha;
;             }
.Lw1_join:
	s_cmp_eq_u32 s63, s64
	s_waitcnt lgkmcnt(0)
	s_barrier
	s_cbranch_scc1 .LBB0_1086
	s_branch .LBB0_1079
.Lfold_0_upd:
	s_cmp_eq_u32 s64, 0
	s_cbranch_scc1 .Lfold_0_first
	v_max_f32_e32 v237, 0, v237
	v_exp_f32_e64 v196, -v237
	s_branch .Lfold_0_go

; DI void attn_unit(LAS unsigned char* lds, int wid, int b, int h, int qb) {
;     ...
;             const float mnew = fmaxf(mrow, mx), alpha = __builtin_amdgcn_exp2f(mrow - mnew); mrow = mnew;
;             float ls = 0.f;
; #pragma unroll
;             for (int i = 0; i < 16; ++i) { s0[i] = __builtin_amdgcn_exp2f(s0[i] - mnew); s1[i] = __builtin_amdgcn_exp2f(s1[i] - mnew); ls += s0[i] + s1[i]; }
;             lrow = lrow * alpha + ls;
;             if (__builtin_amdgcn_ballot_w64(alpha != 1.f) != 0ull) {
; #pragma unroll
;                 for (int dt = 0; dt < 4; ++dt)
; #pragma unroll
;                     for (int i = 0; i < 16; ++i) o[dt][i] *= alpha;
;             }
.Lfold_0_go:
	s_nop 0
	v_pk_mul_f32 v[64:65], v[64:65], v[196:197] op_sel_hi:[1,0]
	v_pk_mul_f32 v[62:63], v[62:63], v[196:197] op_sel_hi:[1,0]
	v_pk_mul_f32 v[60:61], v[60:61], v[196:197] op_sel_hi:[1,0]
	v_pk_mul_f32 v[58:59], v[58:59], v[196:197] op_sel_hi:[1,0]
	v_pk_mul_f32 v[56:57], v[56:57], v[196:197] op_sel_hi:[1,0]
	v_pk_mul_f32 v[54:55], v[54:55], v[196:197] op_sel_hi:[1,0]
	v_pk_mul_f32 v[52:53], v[52:53], v[196:197] op_sel_hi:[1,0]
	v_pk_mul_f32 v[50:51], v[50:51], v[196:197] op_sel_hi:[1,0]
	v_pk_mul_f32 v[48:49], v[48:49], v[196:197] op_sel_hi:[1,0]
	v_pk_mul_f32 v[46:47], v[46:47], v[196:197] op_sel_hi:[1,0]
	v_pk_mul_f32 v[44:45], v[44:45], v[196:197] op_sel_hi:[1,0]
	v_pk_mul_f32 v[42:43], v[42:43], v[196:197] op_sel_hi:[1,0]
	v_pk_mul_f32 v[40:41], v[40:41], v[196:197] op_sel_hi:[1,0]
	v_pk_mul_f32 v[38:39], v[38:39], v[196:197] op_sel_hi:[1,0]
	v_pk_mul_f32 v[36:37], v[36:37], v[196:197] op_sel_hi:[1,0]
	v_pk_mul_f32 v[34:35], v[34:35], v[196:197] op_sel_hi:[1,0]
	v_pk_mul_f32 v[32:33], v[32:33], v[196:197] op_sel_hi:[1,0]
	v_pk_mul_f32 v[30:31], v[30:31], v[196:197] op_sel_hi:[1,0]
	v_pk_mul_f32 v[28:29], v[28:29], v[196:197] op_sel_hi:[1,0]
	v_pk_mul_f32 v[26:27], v[26:27], v[196:197] op_sel_hi:[1,0]
	v_pk_mul_f32 v[24:25], v[24:25], v[196:197] op_sel_hi:[1,0]
	v_pk_mul_f32 v[22:23], v[22:23], v[196:197] op_sel_hi:[1,0]
	v_pk_mul_f32 v[20:21], v[20:21], v[196:197] op_sel_hi:[1,0]
	v_pk_mul_f32 v[18:19], v[18:19], v[196:197] op_sel_hi:[1,0]
	v_pk_mul_f32 v[16:17], v[16:17], v[196:197] op_sel_hi:[1,0]
	v_pk_mul_f32 v[14:15], v[14:15], v[196:197] op_sel_hi:[1,0]
	v_pk_mul_f32 v[12:13], v[12:13], v[196:197] op_sel_hi:[1,0]
	v_pk_mul_f32 v[10:11], v[10:11], v[196:197] op_sel_hi:[1,0]
	v_pk_mul_f32 v[8:9], v[8:9], v[196:197] op_sel_hi:[1,0]
	v_pk_mul_f32 v[6:7], v[6:7], v[196:197] op_sel_hi:[1,0]
	v_pk_mul_f32 v[4:5], v[4:5], v[196:197] op_sel_hi:[1,0]
	v_pk_mul_f32 v[2:3], v[2:3], v[196:197] op_sel_hi:[1,0]
	v_sub_f32_e32 v66, v66, v237
	v_sub_f32_e32 v82, v82, v237
	v_sub_f32_e32 v67, v67, v237
	v_sub_f32_e32 v83, v83, v237
	v_sub_f32_e32 v68, v68, v237
	v_sub_f32_e32 v84, v84, v237
	v_sub_f32_e32 v69, v69, v237
	v_sub_f32_e32 v85, v85, v237
	v_sub_f32_e32 v70, v70, v237
	v_sub_f32_e32 v86, v86, v237
	v_sub_f32_e32 v71, v71, v237
	v_sub_f32_e32 v87, v87, v237
	v_sub_f32_e32 v72, v72, v237
	v_sub_f32_e32 v88, v88, v237
	v_sub_f32_e32 v73, v73, v237
	v_sub_f32_e32 v89, v89, v237
	v_sub_f32_e32 v74, v74, v237
	v_sub_f32_e32 v90, v90, v237
	v_sub_f32_e32 v75, v75, v237
	v_sub_f32_e32 v91, v91, v237
	v_sub_f32_e32 v76, v76, v237
	v_sub_f32_e32 v92, v92, v237
	v_sub_f32_e32 v77, v77, v237
	v_sub_f32_e32 v93, v93, v237
	v_sub_f32_e32 v78, v78, v237
	v_sub_f32_e32 v94, v94, v237
	v_sub_f32_e32 v79, v79, v237
	v_sub_f32_e32 v95, v95, v237
	v_sub_f32_e32 v80, v80, v237
	v_sub_f32_e32 v96, v96, v237
	v_sub_f32_e32 v81, v81, v237
	v_sub_f32_e32 v97, v97, v237
	v_sub_f32_e32 v216, v216, v237
	v_sub_f32_e32 v217, v217, v237
	v_sub_f32_e32 v218, v218, v237
	v_sub_f32_e32 v219, v219, v237
	v_sub_f32_e32 v220, v220, v237
	v_sub_f32_e32 v221, v221, v237
	v_sub_f32_e32 v222, v222, v237
	v_sub_f32_e32 v223, v223, v237
	v_sub_f32_e32 v224, v224, v237
	v_sub_f32_e32 v225, v225, v237
	v_sub_f32_e32 v226, v226, v237
	v_sub_f32_e32 v227, v227, v237
	v_sub_f32_e32 v228, v228, v237
	v_sub_f32_e32 v229, v229, v237
	v_sub_f32_e32 v230, v230, v237
	v_sub_f32_e32 v231, v231, v237
	v_mul_f32_e32 v187, v187, v196
	s_branch .LBB0_1082

; #define LAS __attribute__((address_space(3)))
; DI float shfl_xor_l(float v, int lane, int m) { return __int_as_float(__builtin_amdgcn_ds_bpermute((lane ^ m) << 2, __float_as_int(v))); }
; #define A_LOAD(kt) do { const size_t ko = (size_t)(kt) * 64; st0 = *(const u32x4*)(kn_src + ko * 2048); st1 = *(const u32x4*)(kn_src + (ko + 32) * 2048); \
;         st2 = *(const u32x4*)(kr_src + ko * 64); st3 = *(const u32x4*)(v_src + ko); st4 = *(const u32x4*)(v_src + ko + (size_t)64 * 8192); } while (0)
; #define VLD(dst, j, dt) do { LAS unsigned char* va_ = vb + (32 * (dt) + n) * VROW + (16 * (j) + 4 * g) * 2; const u32x2 lo_ = *(const LAS u32x2*)(va_), hi_ = *(const LAS u32x2*)(va_ + 16); dst = (u32x4){lo_.x, lo_.y, hi_.x, hi_.y}; } while (0)
; DI void attn_unit(LAS unsigned char* lds, int wid, int b, int h, int qb) {
;     ...
;         if (kt + 1 < nkt) A_LOAD(kt + 1);
;         if (kt <= cq) {
;             LAS unsigned char* kb = lds + buf * ABUF; LAS unsigned char* vb = kb + KBYTES;
;             f32x16 s0, s1;
; #pragma unroll
;             for (int i = 0; i < 16; ++i) { s0[i] = 0.f; s1[i] = 0.f; }
;     ...
;             bf16x8 ka[3][2];
;             ka[0][0] = KLD(0, 0); ka[0][1] = KLD(0, 1); ka[1][0] = KLD(1, 0); ka[1][1] = KLD(1, 1);
; #pragma unroll
;             for (int ks = 0; ks < 12; ++ks) {
;                 if (ks + 2 < 12) { ka[(ks + 2) % 3][0] = KLD(ks + 2, 0); ka[(ks + 2) % 3][1] = KLD(ks + 2, 1); }
;                 s0 = __builtin_amdgcn_mfma_f32_32x32x16_bf16(ka[ks % 3][0], qf[ks], s0, 0, 0, 0); s1 = __builtin_amdgcn_mfma_f32_32x32x16_bf16(ka[ks % 3][1], qf[ks], s1, 0, 0, 0);
;                 __builtin_amdgcn_sched_barrier(0); }
;             u32x4 vf[2][4];
; #pragma unroll
;             for (int dt = 0; dt < 4; ++dt) VLD(vf[0][dt], 0, dt);
;             float mx = s0[0];
; #pragma unroll
;             for (int i = 1; i < 16; ++i) mx = fmaxf(mx, s0[i]);
; #pragma unroll
;             for (int i = 0; i < 16; ++i) mx = fmaxf(mx, s1[i]);
;             mx = fmaxf(mx, shfl_xor_l(mx, lane, 32));
;             const float mnew = fmaxf(mrow, mx), alpha = __builtin_amdgcn_exp2f(mrow - mnew); mrow = mnew;
;             float ls = 0.f;
; #pragma unroll
;             for (int i = 0; i < 16; ++i) { s0[i] = __builtin_amdgcn_exp2f(s0[i] - mnew); s1[i] = __builtin_amdgcn_exp2f(s1[i] - mnew); ls += s0[i] + s1[i]; }
.LBB0_1091:
	s_and_b32 s18, s57, 1
	global_load_dwordx4 v[2:5], v198, s[70:71]
	global_load_dwordx4 v[6:9], v198, s[72:73]
	global_load_dwordx4 v[10:13], v196, s[78:79]
	global_load_dwordx4 v[160:163], v194, s[74:75] offset:128
	global_load_dwordx4 v[164:167], v194, s[76:77] offset:128
	s_cmp_gt_u32 s57, s25
	s_cbranch_scc1 .LBB0_1095
	s_mul_i32 s19, s18, 0xa800
	s_add_i32 s19, s19, 0
	v_add3_u32 v0, s19, v193, v204
	ds_read_b128 v[80:83], v0
	ds_read_b128 v[168:171], v0 offset:32
	ds_read_b128 v[96:99], v0 offset:12800
	ds_read_b128 v[174:177], v0 offset:64
	ds_read_b128 v[178:181], v0 offset:12832
	ds_read_b128 v[206:209], v0 offset:12864
	s_waitcnt vmcnt(6) lgkmcnt(3)
	v_mfma_f32_32x32x16_bf16 v[96:111], v[96:99], v[156:159], v[216:231]
	v_mfma_f32_32x32x16_bf16 v[80:95], v[80:83], v[156:159], v[216:231]
	v_mfma_f32_32x32x16_bf16 v[80:95], v[168:171], v[152:155], v[80:95]
	ds_read_b128 v[168:171], v0 offset:96
	ds_read_b128 v[210:213], v0 offset:12896
	s_waitcnt lgkmcnt(3)
	v_mfma_f32_32x32x16_bf16 v[96:111], v[178:181], v[152:155], v[96:111]
	v_mfma_f32_32x32x16_bf16 v[80:95], v[174:177], v[148:151], v[80:95]
	ds_read_b128 v[174:177], v0 offset:128
	ds_read_b128 v[178:181], v0 offset:12928
	s_waitcnt lgkmcnt(4)
	v_mfma_f32_32x32x16_bf16 v[96:111], v[206:209], v[148:151], v[96:111]
	s_waitcnt lgkmcnt(3)
	v_mfma_f32_32x32x16_bf16 v[80:95], v[168:171], v[144:147], v[80:95]
	ds_read_b128 v[168:171], v0 offset:160
	ds_read_b128 v[206:209], v0 offset:12960
	s_waitcnt lgkmcnt(4)
	v_mfma_f32_32x32x16_bf16 v[96:111], v[210:213], v[144:147], v[96:111]
	s_waitcnt lgkmcnt(3)
	v_mfma_f32_32x32x16_bf16 v[80:95], v[174:177], v[140:143], v[80:95]
	ds_read_b128 v[174:177], v0 offset:192
	ds_read_b128 v[210:213], v0 offset:12992
	s_waitcnt lgkmcnt(4)
	v_mfma_f32_32x32x16_bf16 v[96:111], v[178:181], v[140:143], v[96:111]
	s_waitcnt lgkmcnt(3)
	v_mfma_f32_32x32x16_bf16 v[80:95], v[168:171], v[136:139], v[80:95]
	ds_read_b128 v[168:171], v0 offset:224
	ds_read_b128 v[178:181], v0 offset:13024
	s_waitcnt lgkmcnt(4)
	v_mfma_f32_32x32x16_bf16 v[96:111], v[206:209], v[136:139], v[96:111]
	s_waitcnt lgkmcnt(3)
	v_mfma_f32_32x32x16_bf16 v[80:95], v[174:177], v[132:135], v[80:95]
	ds_read_b128 v[174:177], v0 offset:256
	ds_read_b128 v[206:209], v0 offset:13056
	s_waitcnt lgkmcnt(4)
	v_mfma_f32_32x32x16_bf16 v[96:111], v[210:213], v[132:135], v[96:111]
	s_waitcnt lgkmcnt(3)
	v_mfma_f32_32x32x16_bf16 v[80:95], v[168:171], v[128:131], v[80:95]
	ds_read_b128 v[168:171], v0 offset:288
	ds_read_b128 v[210:213], v0 offset:13088
	s_waitcnt lgkmcnt(4)
	v_mfma_f32_32x32x16_bf16 v[96:111], v[178:181], v[128:131], v[96:111]
	s_waitcnt lgkmcnt(3)
	v_mfma_f32_32x32x16_bf16 v[80:95], v[174:177], v[124:127], v[80:95]
	ds_read_b128 v[174:177], v0 offset:320
	ds_read_b128 v[178:181], v0 offset:13120
	s_waitcnt lgkmcnt(4)
	v_mfma_f32_32x32x16_bf16 v[96:111], v[206:209], v[124:127], v[96:111]
	s_waitcnt lgkmcnt(3)
	v_mfma_f32_32x32x16_bf16 v[80:95], v[168:171], v[120:123], v[80:95]
	ds_read_b128 v[168:171], v0 offset:352
	ds_read_b128 v[206:209], v0 offset:13152
	s_waitcnt lgkmcnt(4)
	v_mfma_f32_32x32x16_bf16 v[96:111], v[210:213], v[120:123], v[96:111]
	s_waitcnt lgkmcnt(3)
	v_mfma_f32_32x32x16_bf16 v[80:95], v[174:177], v[116:119], v[80:95]
	s_waitcnt lgkmcnt(2)
	v_mfma_f32_32x32x16_bf16 v[96:111], v[178:181], v[116:119], v[96:111]
	s_waitcnt vmcnt(5) lgkmcnt(1)
	v_mfma_f32_32x32x16_bf16 v[80:95], v[168:171], v[112:115], v[80:95]
	v_add_u32_e32 v0, s19, v188
	v_add_u32_e32 v173, v0, v191
	v_add_u32_e32 v15, 0x6000, v173
	v_add_u32_e32 v205, 0x7000, v173
	ds_read2_b64 v[168:171], v15 offset0:128 offset1:130
	ds_read2_b64 v[180:183], v205 offset0:160 offset1:162
	s_nop 5
	v_max_f32_e32 v0, v80, v81
	s_waitcnt lgkmcnt(2)
	v_mfma_f32_32x32x16_bf16 v[96:111], v[206:209], v[112:115], v[96:111]
	v_max3_f32 v0, v0, v82, v83
	v_max3_f32 v0, v0, v84, v85
	v_max3_f32 v0, v0, v86, v87
	v_max3_f32 v0, v0, v88, v89
	v_max3_f32 v0, v0, v90, v91
	v_max3_f32 v0, v0, v92, v93
	v_max3_f32 v0, v0, v94, v95
	s_nop 4
	v_max3_f32 v0, v0, v96, v97
	v_max3_f32 v0, v0, v98, v99
	v_max3_f32 v0, v0, v100, v101
	v_max3_f32 v0, v0, v102, v103
	v_max3_f32 v0, v0, v104, v105
	v_max3_f32 v0, v0, v106, v107
	v_max3_f32 v0, v0, v108, v109
	v_max3_f32 v0, v0, v110, v111
	ds_bpermute_b32 v14, v189, v0
	v_add_u32_e32 v206, 0x8000, v173
	v_add_u32_e32 v207, 0x9000, v173
	ds_read2_b64 v[176:179], v206 offset0:192 offset1:194
	s_waitcnt lgkmcnt(1)
	v_max_f32_e32 v237, v0, v14
	v_cmp_lt_f32_e32 vcc, 0x41000000, v237
	ds_read2_b64 v[172:175], v207 offset0:224 offset1:226
	s_cmp_eq_u32 s57, 0
	s_cbranch_scc1 .Lfold_2_upd
	s_cbranch_vccnz .Lfold_2_upd
.LBB0_1094:
	v_exp_f32_e32 v80, v80
	v_exp_f32_e32 v96, v96
	v_exp_f32_e32 v81, v81
	v_exp_f32_e32 v97, v97
	v_exp_f32_e32 v82, v82
	v_exp_f32_e32 v98, v98
	v_exp_f32_e32 v83, v83
	v_exp_f32_e32 v99, v99
	v_add_f32_e32 v208, v96, v80
	v_exp_f32_e32 v84, v84
	v_exp_f32_e32 v100, v100

; DI unsigned pk2(float a, float b) { f32x2 f = {a, b}; bf16v2 r = __builtin_convertvector(f, bf16v2); return __builtin_bit_cast(unsigned, r); }
; #define VLD(dst, j, dt) do { LAS unsigned char* va_ = vb + (32 * (dt) + n) * VROW + (16 * (j) + 4 * g) * 2; const u32x2 lo_ = *(const LAS u32x2*)(va_), hi_ = *(const LAS u32x2*)(va_ + 16); dst = (u32x4){lo_.x, lo_.y, hi_.x, hi_.y}; } while (0)
; DI void attn_unit(LAS unsigned char* lds, int wid, int b, int h, int qb) {
;     ...
;             for (int i = 0; i < 16; ++i) { s0[i] = __builtin_amdgcn_exp2f(s0[i] - mnew); s1[i] = __builtin_amdgcn_exp2f(s1[i] - mnew); ls += s0[i] + s1[i]; }
;             lrow = lrow * alpha + ls;
;             if (__builtin_amdgcn_ballot_w64(alpha != 1.f) != 0ull) {
; #pragma unroll
;                 for (int dt = 0; dt < 4; ++dt)
; #pragma unroll
;                     for (int i = 0; i < 16; ++i) o[dt][i] *= alpha;
;             }
;             bf16x8 pf[4];
; #pragma unroll
;             for (int jj = 0; jj < 2; ++jj) { u32x4 w0, w1;
;                 w0.x = pk2(s0[8 * jj + 0], s0[8 * jj + 1]); w0.y = pk2(s0[8 * jj + 2], s0[8 * jj + 3]); w0.z = pk2(s0[8 * jj + 4], s0[8 * jj + 5]); w0.w = pk2(s0[8 * jj + 6], s0[8 * jj + 7]);
;                 w1.x = pk2(s1[8 * jj + 0], s1[8 * jj + 1]); w1.y = pk2(s1[8 * jj + 2], s1[8 * jj + 3]); w1.z = pk2(s1[8 * jj + 4], s1[8 * jj + 5]); w1.w = pk2(s1[8 * jj + 6], s1[8 * jj + 7]);
;                 pf[jj] = __builtin_bit_cast(bf16x8, w0); pf[2 + jj] = __builtin_bit_cast(bf16x8, w1); }
; #pragma unroll
;             for (int j = 0; j < 4; ++j) {
;                 if (j < 3) {
; #pragma unroll
;                     for (int dt = 0; dt < 4; ++dt) VLD(vf[(j + 1) & 1][dt], j + 1, dt);
;                 }
; #pragma unroll
;                 for (int dt = 0; dt < 4; ++dt) o[dt] = __builtin_amdgcn_mfma_f32_32x32x16_bf16(__builtin_bit_cast(bf16x8, vf[j & 1][dt]), pf[j], o[dt], 0, 0, 0);
;                 __builtin_amdgcn_sched_barrier(0); }
	v_add_f32_e32 v209, v97, v81
	v_exp_f32_e32 v85, v85
	v_exp_f32_e32 v101, v101
	v_add_f32_e32 v208, v209, v208
	v_add_f32_e32 v209, v98, v82
	v_exp_f32_e32 v86, v86
	v_exp_f32_e32 v102, v102
	v_add_f32_e32 v208, v209, v208
	v_add_f32_e32 v209, v99, v83
	v_exp_f32_e32 v87, v87
	v_exp_f32_e32 v103, v103
	v_add_f32_e32 v208, v209, v208
	v_add_f32_e32 v209, v100, v84
	v_exp_f32_e32 v88, v88
	v_exp_f32_e32 v104, v104
	v_add_f32_e32 v208, v209, v208
	v_add_f32_e32 v209, v101, v85
	v_exp_f32_e32 v89, v89
	v_exp_f32_e32 v105, v105
	v_add_f32_e32 v208, v209, v208
	v_add_f32_e32 v209, v102, v86
	v_exp_f32_e32 v90, v90
	v_exp_f32_e32 v106, v106
	v_add_f32_e32 v208, v209, v208
	v_add_f32_e32 v209, v103, v87
	v_exp_f32_e32 v91, v91
	v_exp_f32_e32 v107, v107
	v_add_f32_e32 v208, v209, v208
	v_add_f32_e32 v209, v104, v88
	v_exp_f32_e32 v92, v92
	v_exp_f32_e32 v108, v108
	v_add_f32_e32 v208, v209, v208
	v_add_f32_e32 v209, v105, v89
	v_exp_f32_e32 v93, v93
	v_exp_f32_e32 v109, v109
	v_add_f32_e32 v208, v209, v208
	v_add_f32_e32 v209, v106, v90
	v_exp_f32_e32 v94, v94
	v_exp_f32_e32 v110, v110
	v_add_f32_e32 v208, v209, v208
	v_add_f32_e32 v209, v107, v91
	v_exp_f32_e32 v95, v95
	v_exp_f32_e32 v111, v111
	v_add_f32_e32 v208, v209, v208
	v_add_f32_e32 v209, v108, v92
	v_add_f32_e32 v208, v209, v208
	v_add_f32_e32 v209, v109, v93
	v_add_f32_e32 v208, v209, v208
	v_cvt_pk_bf16_f32 v80, v80, v81
	v_cvt_pk_bf16_f32 v81, v82, v83
	v_cvt_pk_bf16_f32 v82, v84, v85
	v_cvt_pk_bf16_f32 v83, v86, v87
	v_add_f32_e32 v84, v110, v94
	v_add_f32_e32 v84, v84, v208
	v_mfma_f32_32x32x16_bf16 v[64:79], v[168:171], v[80:83], v[64:79]
	v_add_f32_e32 v85, v111, v95
	v_add_f32_e32 v168, v85, v84
	v_cvt_pk_bf16_f32 v84, v96, v97
	v_cvt_pk_bf16_f32 v85, v98, v99
	v_cvt_pk_bf16_f32 v86, v100, v101
	v_cvt_pk_bf16_f32 v87, v102, v103
	v_cvt_pk_bf16_f32 v88, v88, v89
	v_mfma_f32_32x32x16_bf16 v[48:63], v[180:183], v[80:83], v[48:63]
	v_cvt_pk_bf16_f32 v89, v90, v91
	v_cvt_pk_bf16_f32 v90, v92, v93
	v_cvt_pk_bf16_f32 v91, v94, v95
	v_cvt_pk_bf16_f32 v92, v104, v105
	v_cvt_pk_bf16_f32 v93, v106, v107
	v_cvt_pk_bf16_f32 v94, v108, v109
	v_cvt_pk_bf16_f32 v95, v110, v111
	s_waitcnt lgkmcnt(1)
	v_mfma_f32_32x32x16_bf16 v[32:47], v[176:179], v[80:83], v[32:47]
	ds_read2_b64 v[96:99], v15 offset0:132 offset1:134
	ds_read2_b64 v[100:103], v205 offset0:164 offset1:166
	ds_read2_b64 v[104:107], v206 offset0:196 offset1:198
	ds_read2_b64 v[108:111], v207 offset0:228 offset1:230
	v_add_f32_e32 v185, v185, v168
	s_waitcnt lgkmcnt(4)
	v_mfma_f32_32x32x16_bf16 v[16:31], v[172:175], v[80:83], v[16:31]
	s_waitcnt lgkmcnt(3)
	v_mfma_f32_32x32x16_bf16 v[64:79], v[96:99], v[88:91], v[64:79]
	s_waitcnt lgkmcnt(2)
	v_mfma_f32_32x32x16_bf16 v[48:63], v[100:103], v[88:91], v[48:63]
	s_waitcnt lgkmcnt(1)
	v_mfma_f32_32x32x16_bf16 v[32:47], v[104:107], v[88:91], v[32:47]
	ds_read2_b64 v[80:83], v15 offset0:136 offset1:138
	ds_read2_b64 v[96:99], v205 offset0:168 offset1:170
	ds_read2_b64 v[100:103], v206 offset0:200 offset1:202
	ds_read2_b64 v[104:107], v207 offset0:232 offset1:234
	s_waitcnt lgkmcnt(4)
	v_mfma_f32_32x32x16_bf16 v[16:31], v[108:111], v[88:91], v[16:31]
	s_waitcnt lgkmcnt(3)
	v_mfma_f32_32x32x16_bf16 v[64:79], v[80:83], v[84:87], v[64:79]
	s_waitcnt lgkmcnt(2)
	v_mfma_f32_32x32x16_bf16 v[48:63], v[96:99], v[84:87], v[48:63]
	s_waitcnt lgkmcnt(1)
	v_mfma_f32_32x32x16_bf16 v[32:47], v[100:103], v[84:87], v[32:47]
	ds_read2_b64 v[80:83], v15 offset0:140 offset1:142
	ds_read2_b64 v[88:91], v205 offset0:172 offset1:174
	ds_read2_b64 v[96:99], v206 offset0:204 offset1:206
	ds_read2_b64 v[100:103], v207 offset0:236 offset1:238
	s_waitcnt lgkmcnt(4)
	v_mfma_f32_32x32x16_bf16 v[16:31], v[104:107], v[84:87], v[16:31]
	s_waitcnt lgkmcnt(3)
	v_mfma_f32_32x32x16_bf16 v[64:79], v[80:83], v[92:95], v[64:79]
	s_waitcnt lgkmcnt(2)
	v_mfma_f32_32x32x16_bf16 v[48:63], v[88:91], v[92:95], v[48:63]
	s_waitcnt lgkmcnt(1)
	v_mfma_f32_32x32x16_bf16 v[32:47], v[96:99], v[92:95], v[32:47]
	s_waitcnt lgkmcnt(0)
	v_mfma_f32_32x32x16_bf16 v[16:31], v[100:103], v[92:95], v[16:31]

; DI void attn_unit(LAS unsigned char* lds, int wid, int b, int h, int qb) {
;     ...
;             const float mnew = fmaxf(mrow, mx), alpha = __builtin_amdgcn_exp2f(mrow - mnew); mrow = mnew;
;             float ls = 0.f;
; #pragma unroll
;             for (int i = 0; i < 16; ++i) { s0[i] = __builtin_amdgcn_exp2f(s0[i] - mnew); s1[i] = __builtin_amdgcn_exp2f(s1[i] - mnew); ls += s0[i] + s1[i]; }
;             lrow = lrow * alpha + ls;
;             if (__builtin_amdgcn_ballot_w64(alpha != 1.f) != 0ull) {
; #pragma unroll
;                 for (int dt = 0; dt < 4; ++dt)
; #pragma unroll
;                     for (int i = 0; i < 16; ++i) o[dt][i] *= alpha;
;             }
.Lw2_join:
	s_cmp_eq_u32 s4, s57
	s_waitcnt lgkmcnt(0)
	s_barrier
	s_cbranch_scc1 .LBB0_1098
	s_branch .LBB0_1091
.Lfold_2_upd:
	s_cmp_eq_u32 s57, 0
	s_cbranch_scc1 .Lfold_2_first
	v_max_f32_e32 v237, 0, v237
	v_exp_f32_e64 v0, -v237
	s_branch .Lfold_2_go

; DI void attn_unit(LAS unsigned char* lds, int wid, int b, int h, int qb) {
;     ...
;             const float mnew = fmaxf(mrow, mx), alpha = __builtin_amdgcn_exp2f(mrow - mnew); mrow = mnew;
;             float ls = 0.f;
; #pragma unroll
;             for (int i = 0; i < 16; ++i) { s0[i] = __builtin_amdgcn_exp2f(s0[i] - mnew); s1[i] = __builtin_amdgcn_exp2f(s1[i] - mnew); ls += s0[i] + s1[i]; }
;             lrow = lrow * alpha + ls;
;             if (__builtin_amdgcn_ballot_w64(alpha != 1.f) != 0ull) {
; #pragma unroll
;                 for (int dt = 0; dt < 4; ++dt)
; #pragma unroll
;                     for (int i = 0; i < 16; ++i) o[dt][i] *= alpha;
;             }
.Lfold_2_go:
	s_nop 0
	v_pk_mul_f32 v[78:79], v[78:79], v[0:1] op_sel_hi:[1,0]
	v_pk_mul_f32 v[76:77], v[76:77], v[0:1] op_sel_hi:[1,0]
	v_pk_mul_f32 v[74:75], v[74:75], v[0:1] op_sel_hi:[1,0]
	v_pk_mul_f32 v[72:73], v[72:73], v[0:1] op_sel_hi:[1,0]
	v_pk_mul_f32 v[70:71], v[70:71], v[0:1] op_sel_hi:[1,0]
	v_pk_mul_f32 v[68:69], v[68:69], v[0:1] op_sel_hi:[1,0]
	v_pk_mul_f32 v[66:67], v[66:67], v[0:1] op_sel_hi:[1,0]
	v_pk_mul_f32 v[64:65], v[64:65], v[0:1] op_sel_hi:[1,0]
	v_pk_mul_f32 v[62:63], v[62:63], v[0:1] op_sel_hi:[1,0]
	v_pk_mul_f32 v[60:61], v[60:61], v[0:1] op_sel_hi:[1,0]
	v_pk_mul_f32 v[58:59], v[58:59], v[0:1] op_sel_hi:[1,0]
	v_pk_mul_f32 v[56:57], v[56:57], v[0:1] op_sel_hi:[1,0]
	v_pk_mul_f32 v[54:55], v[54:55], v[0:1] op_sel_hi:[1,0]
	v_pk_mul_f32 v[52:53], v[52:53], v[0:1] op_sel_hi:[1,0]
	v_pk_mul_f32 v[50:51], v[50:51], v[0:1] op_sel_hi:[1,0]
	v_pk_mul_f32 v[48:49], v[48:49], v[0:1] op_sel_hi:[1,0]
	v_pk_mul_f32 v[46:47], v[46:47], v[0:1] op_sel_hi:[1,0]
	v_pk_mul_f32 v[44:45], v[44:45], v[0:1] op_sel_hi:[1,0]
	v_pk_mul_f32 v[42:43], v[42:43], v[0:1] op_sel_hi:[1,0]
	v_pk_mul_f32 v[40:41], v[40:41], v[0:1] op_sel_hi:[1,0]
	v_pk_mul_f32 v[38:39], v[38:39], v[0:1] op_sel_hi:[1,0]
	v_pk_mul_f32 v[36:37], v[36:37], v[0:1] op_sel_hi:[1,0]
	v_pk_mul_f32 v[34:35], v[34:35], v[0:1] op_sel_hi:[1,0]
	v_pk_mul_f32 v[32:33], v[32:33], v[0:1] op_sel_hi:[1,0]
	v_pk_mul_f32 v[30:31], v[30:31], v[0:1] op_sel_hi:[1,0]
	v_pk_mul_f32 v[28:29], v[28:29], v[0:1] op_sel_hi:[1,0]
	v_pk_mul_f32 v[26:27], v[26:27], v[0:1] op_sel_hi:[1,0]
	v_pk_mul_f32 v[24:25], v[24:25], v[0:1] op_sel_hi:[1,0]
	v_pk_mul_f32 v[22:23], v[22:23], v[0:1] op_sel_hi:[1,0]
	v_pk_mul_f32 v[20:21], v[20:21], v[0:1] op_sel_hi:[1,0]
	v_pk_mul_f32 v[18:19], v[18:19], v[0:1] op_sel_hi:[1,0]
	v_pk_mul_f32 v[16:17], v[16:17], v[0:1] op_sel_hi:[1,0]
	v_sub_f32_e32 v80, v80, v237
	v_sub_f32_e32 v96, v96, v237
	v_sub_f32_e32 v81, v81, v237
	v_sub_f32_e32 v97, v97, v237
	v_sub_f32_e32 v82, v82, v237
	v_sub_f32_e32 v98, v98, v237
	v_sub_f32_e32 v83, v83, v237
	v_sub_f32_e32 v99, v99, v237
	v_sub_f32_e32 v84, v84, v237
	v_sub_f32_e32 v100, v100, v237
	v_sub_f32_e32 v85, v85, v237
	v_sub_f32_e32 v101, v101, v237
	v_sub_f32_e32 v86, v86, v237
	v_sub_f32_e32 v102, v102, v237
	v_sub_f32_e32 v87, v87, v237
	v_sub_f32_e32 v103, v103, v237
	v_sub_f32_e32 v88, v88, v237
	v_sub_f32_e32 v104, v104, v237
	v_sub_f32_e32 v89, v89, v237
	v_sub_f32_e32 v105, v105, v237
	v_sub_f32_e32 v90, v90, v237
	v_sub_f32_e32 v106, v106, v237
	v_sub_f32_e32 v91, v91, v237
	v_sub_f32_e32 v107, v107, v237
	v_sub_f32_e32 v92, v92, v237
	v_sub_f32_e32 v108, v108, v237
	v_sub_f32_e32 v93, v93, v237
	v_sub_f32_e32 v109, v109, v237
	v_sub_f32_e32 v94, v94, v237
	v_sub_f32_e32 v110, v110, v237
	v_sub_f32_e32 v95, v95, v237
	v_sub_f32_e32 v111, v111, v237
	v_sub_f32_e32 v216, v216, v237
	v_sub_f32_e32 v217, v217, v237
	v_sub_f32_e32 v218, v218, v237
	v_sub_f32_e32 v219, v219, v237
	v_sub_f32_e32 v220, v220, v237
	v_sub_f32_e32 v221, v221, v237
	v_sub_f32_e32 v222, v222, v237
	v_sub_f32_e32 v223, v223, v237
	v_sub_f32_e32 v224, v224, v237
	v_sub_f32_e32 v225, v225, v237
	v_sub_f32_e32 v226, v226, v237
	v_sub_f32_e32 v227, v227, v237
	v_sub_f32_e32 v228, v228, v237
	v_sub_f32_e32 v229, v229, v237
	v_sub_f32_e32 v230, v230, v237
	v_sub_f32_e32 v231, v231, v237
	v_mul_f32_e32 v185, v185, v0
	s_branch .LBB0_1094
